# P4 attention: gathered-query count kept in a register from the item head; three re-loads (each with a full wait) removed
# speedup vs baseline: 1.0002x; 1.0002x over previous
; DI void phase4(const Params& P, char* smem) {
;     ...
;     int lo = 0, hi = 1024;
;     while (hi - lo > 1) { const int mid = (lo + hi) >> 1; if (pre[mid] <= it) lo = mid; else hi = mid; }
;     const int bh = lo >> 5, n = lo & 31, b = bh >> 3, h = bh & 7;
;     const int ntask = 4 + ((gcount[lo] + 31) >> 5);
;     const int task = (it - pre[lo]) * 8 + wid;
;     uint4 kr[8], vr[8];
; #pragma unroll
;     for (int i = 0; i < 8; ++i) {
;       const int q = i * 256 + tid;
;       kr[i] = *reinterpret_cast<const uint4*>(Kb + ((long)(b * 8192 + n * 256 + (q >> 3))) * 512 + h * 64 + (q & 7) * 8);
;       vr[i] = *reinterpret_cast<const uint4*>(Vt + ((long)(bh * 64 + (q >> 5))) * 8192 + n * 256 + (q & 31) * 8);
;     }
; #pragma unroll
;     for (int i = 0; i < 8; ++i) {
;       const int q = i * 256 + tid, row = q >> 3;
;       *reinterpret_cast<uint4*>(Ks + row * 128 + (((q & 7) ^ ((row >> 1) & 7)) * 16)) = kr[i];
;       *reinterpret_cast<uint4*>(Vs + (q >> 5) * 528 + (q & 31) * 16) = vr[i];
;     }
;     __syncthreads();
.LBB0_769:
	v_add_u32_e32 v2, v0, v66
	v_ashrrev_i32_e32 v2, 1, v2
	v_lshl_add_u32 v3, v2, 2, v92
	ds_read_b32 v3, v3
	s_waitcnt lgkmcnt(0)
	v_cmp_gt_i32_e32 vcc, v3, v144
	s_nop 1
	v_cndmask_b32_e32 v0, v0, v2, vcc
	v_cndmask_b32_e32 v66, v2, v66, vcc
	v_sub_u32_e32 v2, v0, v66
	v_cmp_gt_i32_e32 vcc, 2, v2
	s_or_b64 s[0:1], vcc, s[0:1]
	s_andn2_b64 exec, exec, s[0:1]
	s_cbranch_execnz .LBB0_769
	s_or_b64 exec, exec, s[0:1]
	v_lshlrev_b32_e32 v0, 5, v66
	v_ashrrev_i32_e32 v74, 5, v66
	v_and_b32_e32 v16, 0xffffe000, v0
	v_lshlrev_b32_e32 v0, 8, v66
	v_and_b32_e32 v145, 0x1f00, v0
	v_lshlrev_b32_e32 v17, 6, v74
	v_lshlrev_b32_e32 v0, 7, v74
	v_and_b32_e32 v0, 0x380, v0
	v_or_b32_e32 v12, v17, v102
	v_lshl_add_u64 v[2:3], v[80:81], 0, v[0:1]
	v_lshlrev_b32_e32 v0, 1, v145
	v_ashrrev_i32_e32 v13, 31, v12
	v_lshl_add_u64 v[4:5], v[82:83], 0, v[0:1]
	v_lshlrev_b64 v[12:13], 14, v[12:13]
	v_lshl_add_u64 v[14:15], v[4:5], 0, v[12:13]
	v_or3_b32 v12, v16, v103, v145
	v_ashrrev_i32_e32 v13, 31, v12
	v_lshlrev_b64 v[12:13], 10, v[12:13]
	v_lshl_add_u64 v[18:19], v[2:3], 0, v[12:13]
	v_or_b32_e32 v12, v17, v104
	v_ashrrev_i32_e32 v13, 31, v12
	v_lshlrev_b64 v[12:13], 14, v[12:13]
	v_lshl_add_u64 v[22:23], v[4:5], 0, v[12:13]
	v_or3_b32 v12, v16, v105, v145
	v_ashrrev_i32_e32 v13, 31, v12
	v_lshlrev_b64 v[12:13], 10, v[12:13]
	v_lshl_add_u64 v[26:27], v[2:3], 0, v[12:13]
	v_or_b32_e32 v12, v17, v106
	v_ashrrev_i32_e32 v13, 31, v12
	v_lshlrev_b64 v[12:13], 14, v[12:13]
	v_lshl_add_u64 v[30:31], v[4:5], 0, v[12:13]
	v_or3_b32 v12, v16, v107, v145
	v_ashrrev_i32_e32 v13, 31, v12
	v_lshlrev_b64 v[12:13], 10, v[12:13]
	v_lshl_add_u64 v[34:35], v[2:3], 0, v[12:13]
	v_or_b32_e32 v12, v17, v108
	v_ashrrev_i32_e32 v13, 31, v12
	v_lshlrev_b64 v[12:13], 14, v[12:13]
	v_lshl_add_u64 v[38:39], v[4:5], 0, v[12:13]
	v_or3_b32 v12, v16, v109, v145
	v_ashrrev_i32_e32 v13, 31, v12
	v_lshlrev_b64 v[12:13], 10, v[12:13]
	v_lshl_add_u64 v[42:43], v[2:3], 0, v[12:13]
	v_or_b32_e32 v12, v17, v110
	v_ashrrev_i32_e32 v13, 31, v12
	v_lshlrev_b64 v[12:13], 14, v[12:13]
	v_lshl_add_u64 v[46:47], v[4:5], 0, v[12:13]
	v_or3_b32 v12, v16, v111, v145
	v_ashrrev_i32_e32 v13, 31, v12
	v_lshlrev_b64 v[12:13], 10, v[12:13]
	v_lshl_add_u64 v[50:51], v[2:3], 0, v[12:13]
	v_or_b32_e32 v12, v17, v112
	v_ashrrev_i32_e32 v13, 31, v12
	v_lshlrev_b64 v[12:13], 14, v[12:13]
	v_ashrrev_i32_e32 v67, 31, v66
	v_or3_b32 v6, v16, v175, v145
	v_or3_b32 v10, v16, v101, v145
	v_lshl_add_u64 v[54:55], v[4:5], 0, v[12:13]
	v_or3_b32 v12, v16, v113, v145
	v_lshl_add_u64 v[68:69], v[66:67], 2, s[28:29]
	v_ashrrev_i32_e32 v7, 31, v6
	v_ashrrev_i32_e32 v11, 31, v10
	v_ashrrev_i32_e32 v13, 31, v12
	global_load_dword v70, v[68:69], off
	v_lshlrev_b64 v[6:7], 10, v[6:7]
	v_lshlrev_b64 v[10:11], 10, v[10:11]
	v_lshlrev_b64 v[12:13], 10, v[12:13]
	v_lshl_add_u64 v[6:7], v[2:3], 0, v[6:7]
	v_or_b32_e32 v8, v17, v100
	v_lshl_add_u64 v[10:11], v[2:3], 0, v[10:11]
	v_lshl_add_u64 v[58:59], v[2:3], 0, v[12:13]
	v_or_b32_e32 v2, v17, v114
	v_ashrrev_i32_e32 v9, 31, v8
	v_ashrrev_i32_e32 v3, 31, v2
	v_lshlrev_b64 v[8:9], 14, v[8:9]
	v_lshlrev_b64 v[2:3], 14, v[2:3]
	v_lshl_add_u64 v[8:9], v[4:5], 0, v[8:9]
	v_lshl_add_u64 v[62:63], v[4:5], 0, v[2:3]
	global_load_dwordx4 v[2:5], v[6:7], off
	s_nop 0
	global_load_dwordx4 v[6:9], v[8:9], off
	s_nop 0
	global_load_dwordx4 v[10:13], v[10:11], off
	s_nop 0
	global_load_dwordx4 v[14:17], v[14:15], off
	s_nop 0
	global_load_dwordx4 v[18:21], v[18:19], off
	s_nop 0
	global_load_dwordx4 v[22:25], v[22:23], off
	s_nop 0
	global_load_dwordx4 v[26:29], v[26:27], off
	s_nop 0
	global_load_dwordx4 v[30:33], v[30:31], off
	s_nop 0
	global_load_dwordx4 v[34:37], v[34:35], off
	s_nop 0
	global_load_dwordx4 v[38:41], v[38:39], off
	s_nop 0
	global_load_dwordx4 v[42:45], v[42:43], off
	s_nop 0
	global_load_dwordx4 v[46:49], v[46:47], off
	s_nop 0
	global_load_dwordx4 v[50:53], v[50:51], off
	s_nop 0
	global_load_dwordx4 v[54:57], v[54:55], off
	s_nop 0
	global_load_dwordx4 v[58:61], v[58:59], off
	s_nop 0
	global_load_dwordx4 v[62:65], v[62:63], off
	v_lshl_add_u32 v0, v66, 2, v92
	ds_read_b32 v146, v0
	s_waitcnt vmcnt(15)
	ds_write_b128 v115, v[2:5]
	s_waitcnt vmcnt(14)
	ds_write_b128 v116, v[6:9]
	s_waitcnt vmcnt(13)
	ds_write_b128 v117, v[10:13]
	s_waitcnt vmcnt(12)
	ds_write_b128 v118, v[14:17]
	s_waitcnt vmcnt(11)
	ds_write_b128 v119, v[18:21]
	s_waitcnt vmcnt(10)
	ds_write_b128 v120, v[22:25]
	s_waitcnt vmcnt(9)
	ds_write_b128 v121, v[26:29]
	s_waitcnt vmcnt(8)
	ds_write_b128 v122, v[30:33]
	s_waitcnt vmcnt(7)
	ds_write_b128 v123, v[34:37]
	s_waitcnt vmcnt(6)
	ds_write_b128 v125, v[38:41]
	s_waitcnt vmcnt(5)
	ds_write_b128 v126, v[42:45]
	s_waitcnt vmcnt(4)
	ds_write_b128 v127, v[46:49]
	s_waitcnt vmcnt(3)
	ds_write_b128 v130, v[50:53]
	s_waitcnt vmcnt(2)
	ds_write_b128 v131, v[54:57]
	s_waitcnt vmcnt(1)
	ds_write_b128 v132, v[58:61]
	s_waitcnt vmcnt(0)
	ds_write_b128 v133, v[62:65]
	v_add_u32_e32 v0, 31, v70
	v_mov_b32_e32 v232, v70
	v_ashrrev_i32_e32 v77, 5, v0
	s_waitcnt lgkmcnt(14)
	v_sub_u32_e32 v76, v144, v146
	v_add_u32_e32 v0, 4, v77
	v_lshl_or_b32 v75, v76, 3, v194
	v_cmp_lt_i32_e32 vcc, v75, v0
	s_and_b64 s[0:1], s[6:7], vcc
	s_waitcnt lgkmcnt(0)
	s_barrier
	s_and_saveexec_b64 s[48:49], s[0:1]
	s_cbranch_execz .LBB0_775
	v_cmp_lt_i32_e32 vcc, 3, v75
	s_mov_b64 s[50:51], 0
	s_and_saveexec_b64 s[0:1], vcc
	s_xor_b64 s[24:25], exec, s[0:1]
	s_cbranch_execnz .LBB0_785
	s_andn2_saveexec_b64 s[56:57], s[24:25]
	s_cbranch_execnz .LBB0_801

; DI void attn_task(const Params& P, int bh, int n, int t, int lane, const char* Ks, const char* Vs) {
;     ...
;     const int cnt = gcount[bh * 32 + n], idx = (t - 8) * 32 + r;
;     valid = idx < cnt;
;     const int e = list[((long)(bh * 32 + n)) * 8192 + (valid ? idx : 0)];
;     lq = e >> 2; slot = e & 3;
;   }
; DI void phase4(const Params& P, char* smem) {
;     ...
;     if (act && task < ntask) {
;       if (task < 4) { attn_task(P, bh, n, task, lane, Ks, Vs); attn_task(P, bh, n, 7 - task, lane, Ks, Vs); }
;       else attn_task(P, bh, n, task - 4 + 8, lane, Ks, Vs);
;     }
;     if (act && task + 4 < ntask) attn_task(P, bh, n, task + 4 - 4 + 8, lane, Ks, Vs);
.LBB0_775:
	s_or_b64 exec, exec, s[48:49]
	v_cmp_lt_i32_e32 vcc, v75, v77
	s_and_b64 s[0:1], s[6:7], vcc
	s_and_saveexec_b64 s[20:21], s[0:1]
	s_cbranch_execz .LBB0_767
	v_add_u32_e32 v0, 8, v75
	v_cmp_lt_i32_e32 vcc, -1, v76
	s_and_saveexec_b64 s[0:1], vcc
	s_xor_b64 s[0:1], exec, s[0:1]
	s_cbranch_execz .LBB0_778
	v_mov_b32_e32 v4, v232
	v_lshl_add_u32 v0, v0, 5, v98
	v_lshlrev_b64 v[2:3], 14, v[66:67]
	v_lshl_add_u64 v[2:3], s[30:31], 0, v[2:3]
	v_cmp_lt_i32_e64 s[24:25], v0, v4
	s_nop 1
	v_cndmask_b32_e64 v0, 0, v0, s[24:25]
	v_lshl_add_u64 v[2:3], v[0:1], 1, v[2:3]
	global_load_ushort v0, v[2:3], off
	s_waitcnt vmcnt(0)
	v_lshrrev_b32_e32 v148, 2, v0
	v_and_b32_e32 v88, 3, v0

; DI void attn_task(const Params& P, int bh, int n, int t, int lane, const char* Ks, const char* Vs) {
;     ...
;     const int cnt = gcount[bh * 32 + n], idx = (t - 8) * 32 + r;
;     valid = idx < cnt;
;     const int e = list[((long)(bh * 32 + n)) * 8192 + (valid ? idx : 0)];
;     lq = e >> 2; slot = e & 3;
.LBB0_785:
	v_or_b32_e32 v0, 4, v75
	v_cmp_ne_u32_e32 vcc, v144, v146
	s_and_saveexec_b64 s[0:1], vcc
	s_xor_b64 s[0:1], exec, s[0:1]
	s_cbranch_execz .LBB0_787
	v_mov_b32_e32 v4, v232
	v_lshl_add_u32 v0, v0, 5, v98
	v_lshlrev_b64 v[2:3], 14, v[66:67]
	v_lshl_add_u64 v[2:3], s[30:31], 0, v[2:3]
	v_cmp_lt_i32_e64 s[50:51], v0, v4
	s_nop 1
	v_cndmask_b32_e64 v0, 0, v0, s[50:51]
	v_lshl_add_u64 v[2:3], v[0:1], 1, v[2:3]
	global_load_ushort v0, v[2:3], off
	s_waitcnt vmcnt(0)
	v_lshrrev_b32_e32 v78, 2, v0
	v_and_b32_e32 v70, 3, v0

; DI void attn_task(const Params& P, int bh, int n, int t, int lane, const char* Ks, const char* Vs) {
;     ...
;     const int cnt = gcount[bh * 32 + n], idx = (t - 8) * 32 + r;
;     valid = idx < cnt;
;     const int e = list[((long)(bh * 32 + n)) * 8192 + (valid ? idx : 0)];
;     lq = e >> 2; slot = e & 3;
.LBB0_809:
	s_or_b64 exec, exec, s[0:1]
	v_sub_u32_e32 v2, 7, v75
	v_cmp_gt_i32_e32 vcc, 0, v76
	s_and_saveexec_b64 s[0:1], vcc
	s_xor_b64 s[0:1], exec, s[0:1]
	s_cbranch_execz .LBB0_811
	v_mov_b32_e32 v6, v232
	v_lshl_add_u32 v2, v2, 5, v98
	v_lshlrev_b64 v[4:5], 14, v[66:67]
	v_mov_b32_e32 v3, v1
	v_lshl_add_u64 v[4:5], s[30:31], 0, v[4:5]
	v_cmp_lt_i32_e64 s[24:25], v2, v6
	s_nop 1
	v_cndmask_b32_e64 v2, 0, v2, s[24:25]
	v_lshl_add_u64 v[2:3], v[2:3], 1, v[4:5]
	global_load_ushort v2, v[2:3], off
	s_waitcnt vmcnt(0)
	v_lshrrev_b32_e32 v79, 2, v2
	v_and_b32_e32 v70, 3, v2
